# attention: exp-group/PV MFMA interleave, lazy softmax rescale (threshold 24 in log2 units), hoisted per-tile address math; keeps FFN-down sample-row GEMM K-split
# baseline (speedup 1.0000x reference)
; #define LAS __attribute__((address_space(3)))
; __device__ __forceinline__ unsigned pk_bf16(float lo, float hi) { const f32x2_t v = {lo, hi}; const bf16x2_t b = __builtin_convertvector(v, bf16x2_t); return __builtin_bit_cast(unsigned, b); }
; __device__ __forceinline__ int fresh_tid() { int t = threadIdx.x; asm volatile("" : "+v"(t)); return t; }
; __device__ __forceinline__ void attn_load(const AttnJob& J, int t, u32x4& kreg, u32x4& vreg) {
;     const int tid = fresh_tid(), key = tid >> 3, ch = tid & 7, kidx = 64 * t + key;
;     if (J.mode == 0) { const bf16_t* p = J.Kb + (size_t)kidx * 2048 + ch * 8; kreg = *(const u32x4*)p; vreg = *(const u32x4*)(p + 512); }
;     else if (kidx < PAST) { const float* pk = J.cK + (size_t)kidx * 512 + ch * 8; const float* pv = J.cV + (size_t)kidx * 512 + ch * 8;
;         const f32x4 a = *(const f32x4*)pk, b = *(const f32x4*)(pk + 4), c = *(const f32x4*)pv, d = *(const f32x4*)(pv + 4);
;         kreg = (u32x4){pk_bf16(a.x, a.y), pk_bf16(a.z, a.w), pk_bf16(b.x, b.y), pk_bf16(b.z, b.w)};
;         vreg = (u32x4){pk_bf16(c.x, c.y), pk_bf16(c.z, c.w), pk_bf16(d.x, d.y), pk_bf16(d.z, d.w)}; }
;     else if (kidx < PAST + TS) { const bf16_t* p = J.Kb + (size_t)(kidx - PAST) * 2048 + ch * 8; kreg = *(const u32x4*)p; vreg = *(const u32x4*)(p + 512); }
;     else { kreg = (u32x4){0u, 0u, 0u, 0u}; vreg = kreg; }
; }
; __device__ __forceinline__ void attn_stage(LAS unsigned char* lds, int buf, const u32x4& kreg, const u32x4& vreg) {
;     const int tid = fresh_tid(), key = tid >> 3, ch = tid & 7;
;     *(LAS u32x4*)(lds + AT_K + buf * AT_KB + key * 144 + ch * 16) = kreg;
;     LAS bf16_t* vt = (LAS bf16_t*)(lds + AT_VT + buf * AT_VB) + (ch * 8) * 68 + key;
;     vt[0 * 68] = (bf16_t)(vreg.x & 0xffffu); vt[1 * 68] = (bf16_t)(vreg.x >> 16);
;     vt[2 * 68] = (bf16_t)(vreg.y & 0xffffu); vt[3 * 68] = (bf16_t)(vreg.y >> 16);
;     vt[4 * 68] = (bf16_t)(vreg.z & 0xffffu); vt[5 * 68] = (bf16_t)(vreg.z >> 16);
;     vt[6 * 68] = (bf16_t)(vreg.w & 0xffffu); vt[7 * 68] = (bf16_t)(vreg.w >> 16);
; }
.Lattn_save:
	v_lshrrev_b32_e32 v0, 6, v198
	v_mul_u32_u24_e32 v0, 0x300, v0
	v_and_or_b32 v0, v198, 63, v0
	v_lshlrev_b32_e32 v0, 4, v0
	ds_write_b128 v0, v[124:127] offset:45056
	ds_write_b128 v0, v[128:131] offset:46080
	ds_write_b128 v0, v[132:135] offset:47104
	ds_write_b128 v0, v[136:139] offset:48128
	ds_write_b128 v0, v[140:143] offset:49152
	ds_write_b128 v0, v[144:147] offset:50176
	ds_write_b128 v0, v[148:151] offset:51200
	ds_write_b128 v0, v[152:155] offset:52224
	ds_write_b128 v0, v[156:159] offset:53248
	s_waitcnt lgkmcnt(0)
	v_lshrrev_b32_e32 v0, 3, v198
	v_and_b32_e32 v157, 7, v198
	v_mul_u32_u24_e32 v156, 0x90, v0
	v_lshl_add_u32 v156, v157, 4, v156
	v_lshlrev_b32_e32 v158, 12, v0
	v_lshl_add_u32 v158, v157, 4, v158
	v_mul_u32_u24_e32 v157, 0x440, v157
	v_lshl_add_u32 v157, v0, 1, v157
	v_mov_b32_e32 v159, 0
	s_branch .LBB0_629

; #define LAS __attribute__((address_space(3)))
; __device__ __forceinline__ unsigned pk_bf16(float lo, float hi) { const f32x2_t v = {lo, hi}; const bf16x2_t b = __builtin_convertvector(v, bf16x2_t); return __builtin_bit_cast(unsigned, b); }
; __device__ __forceinline__ float fexp2(float x) { return __builtin_amdgcn_exp2f(x); }
; __device__ __forceinline__ void attn_tile(int t, int buf, LAS unsigned char* lds, const bf16x8 (&qr)[4], float cq2, int qlo, int qpos, int q32, int hi,
;                                           float& mrun, float& lrun, f32x16& o0, f32x16& o1) {
;     ...
;     f32x2 ls2 = (f32x2){0.f, 0.f};
; #pragma unroll
;     for (int r = 0; r < 16; r += 2) {
;         const f32x2 d0 = (f32x2){s0[r], s0[r + 1]} - mnew, d1 = (f32x2){s1[r], s1[r + 1]} - mnew;
;         f32x2 e0, e1; e0.x = fexp2(d0.x); e0.y = fexp2(d0.y); e1.x = fexp2(d1.x); e1.y = fexp2(d1.y);
;         s0[r] = e0.x; s0[r + 1] = e0.y; s1[r] = e1.x; s1[r + 1] = e1.y;
;         ls2 += e0 + e1;
;     }
;     lrun += ls2.x + ls2.y;
; #pragma unroll
;     for (int p = 0; p < 2; ++p)
; #pragma unroll
;         for (int sx = 0; sx < 2; ++sx) {
;             u32x4 pw;
;             if (p == 0) pw = (u32x4){pk_bf16(s0[8 * sx + 0], s0[8 * sx + 1]), pk_bf16(s0[8 * sx + 2], s0[8 * sx + 3]), pk_bf16(s0[8 * sx + 4], s0[8 * sx + 5]), pk_bf16(s0[8 * sx + 6], s0[8 * sx + 7])};
;             else        pw = (u32x4){pk_bf16(s1[8 * sx + 0], s1[8 * sx + 1]), pk_bf16(s1[8 * sx + 2], s1[8 * sx + 3]), pk_bf16(s1[8 * sx + 4], s1[8 * sx + 5]), pk_bf16(s1[8 * sx + 6], s1[8 * sx + 7])};
;             const bf16x8 pf = __builtin_bit_cast(bf16x8, pw);
;             const int ko = (32 * p + 16 * sx + 4 * hi) * 2;
;             const u32x2 a0 = *(const LAS u32x2*)(Vt + q32 * 136 + ko), a1 = *(const LAS u32x2*)(Vt + q32 * 136 + ko + 16);
;             const u32x2 b0 = *(const LAS u32x2*)(Vt + (32 + q32) * 136 + ko), b1 = *(const LAS u32x2*)(Vt + (32 + q32) * 136 + ko + 16);
;             const bf16x8 vf0 = __builtin_bit_cast(bf16x8, (u32x4){a0.x, a0.y, a1.x, a1.y});
;             const bf16x8 vf1 = __builtin_bit_cast(bf16x8, (u32x4){b0.x, b0.y, b1.x, b1.y});
;             o0 = __builtin_amdgcn_mfma_f32_32x32x16_bf16(vf0, pf, o0, 0, 0, 0);
;             o1 = __builtin_amdgcn_mfma_f32_32x32x16_bf16(vf1, pf, o1, 0, 0, 0);
;         }
.LBB0_643:
	v_add_u32_e32 v122, 0x8800, v113
	v_add_u32_e32 v123, 0x9800, v113
	ds_read2_b64 v[124:127], v122 offset0:96 offset1:98
	ds_read2_b64 v[128:131], v123 offset0:128 offset1:130
	ds_read2_b64 v[132:135], v122 offset0:100 offset1:102
	ds_read2_b64 v[136:139], v123 offset0:132 offset1:134
	ds_read2_b64 v[140:143], v122 offset0:104 offset1:106
	ds_read2_b64 v[144:147], v123 offset0:136 offset1:138
	ds_read2_b64 v[148:151], v122 offset0:108 offset1:110
	ds_read2_b64 v[152:155], v123 offset0:140 offset1:142
	v_pk_add_f32 v[34:35], v[34:35], v[0:1] op_sel_hi:[1,0] neg_lo:[0,1] neg_hi:[0,1]
	v_pk_add_f32 v[36:37], v[36:37], v[0:1] op_sel_hi:[1,0] neg_lo:[0,1] neg_hi:[0,1]
	v_pk_add_f32 v[38:39], v[38:39], v[0:1] op_sel_hi:[1,0] neg_lo:[0,1] neg_hi:[0,1]
	v_pk_add_f32 v[40:41], v[40:41], v[0:1] op_sel_hi:[1,0] neg_lo:[0,1] neg_hi:[0,1]
	v_exp_f32_e32 v34, v34
	v_exp_f32_e32 v35, v35
	v_exp_f32_e32 v36, v36
	v_exp_f32_e32 v37, v37
	v_exp_f32_e32 v38, v38
	v_exp_f32_e32 v39, v39
	v_exp_f32_e32 v40, v40
	v_exp_f32_e32 v41, v41
	v_cvt_pk_bf16_f32 v118, v34, v35
	v_cvt_pk_bf16_f32 v119, v36, v37
	v_cvt_pk_bf16_f32 v120, v38, v39
	v_cvt_pk_bf16_f32 v121, v40, v41
	v_pk_add_f32 v[116:117], v[34:35], v[36:37]
	v_pk_add_f32 v[38:39], v[38:39], v[40:41]
	v_pk_add_f32 v[116:117], v[116:117], v[38:39]
	s_waitcnt lgkmcnt(0)
	v_mfma_f32_32x32x16_bf16 v[18:33], v[124:127], v[118:121], v[18:33]
	v_mfma_f32_32x32x16_bf16 v[2:17], v[128:131], v[118:121], v[2:17]
	v_pk_add_f32 v[42:43], v[42:43], v[0:1] op_sel_hi:[1,0] neg_lo:[0,1] neg_hi:[0,1]
	v_pk_add_f32 v[44:45], v[44:45], v[0:1] op_sel_hi:[1,0] neg_lo:[0,1] neg_hi:[0,1]
	v_pk_add_f32 v[46:47], v[46:47], v[0:1] op_sel_hi:[1,0] neg_lo:[0,1] neg_hi:[0,1]
	v_pk_add_f32 v[48:49], v[48:49], v[0:1] op_sel_hi:[1,0] neg_lo:[0,1] neg_hi:[0,1]
	v_exp_f32_e32 v42, v42
	v_exp_f32_e32 v43, v43
	v_exp_f32_e32 v44, v44
	v_exp_f32_e32 v45, v45
	v_exp_f32_e32 v46, v46
	v_exp_f32_e32 v47, v47
	v_exp_f32_e32 v48, v48
	v_exp_f32_e32 v49, v49
	v_cvt_pk_bf16_f32 v118, v42, v43
	v_cvt_pk_bf16_f32 v119, v44, v45
	v_cvt_pk_bf16_f32 v120, v46, v47
	v_cvt_pk_bf16_f32 v121, v48, v49
	v_pk_add_f32 v[42:43], v[42:43], v[44:45]
	v_pk_add_f32 v[46:47], v[46:47], v[48:49]
	v_pk_add_f32 v[42:43], v[42:43], v[46:47]
	v_pk_add_f32 v[116:117], v[116:117], v[42:43]
	v_mfma_f32_32x32x16_bf16 v[18:33], v[132:135], v[118:121], v[18:33]
	v_mfma_f32_32x32x16_bf16 v[2:17], v[136:139], v[118:121], v[2:17]
	v_pk_add_f32 v[50:51], v[50:51], v[0:1] op_sel_hi:[1,0] neg_lo:[0,1] neg_hi:[0,1]
	v_pk_add_f32 v[52:53], v[52:53], v[0:1] op_sel_hi:[1,0] neg_lo:[0,1] neg_hi:[0,1]
	v_pk_add_f32 v[54:55], v[54:55], v[0:1] op_sel_hi:[1,0] neg_lo:[0,1] neg_hi:[0,1]
	v_pk_add_f32 v[56:57], v[56:57], v[0:1] op_sel_hi:[1,0] neg_lo:[0,1] neg_hi:[0,1]
	v_exp_f32_e32 v50, v50
	v_exp_f32_e32 v51, v51
	v_exp_f32_e32 v52, v52
	v_exp_f32_e32 v53, v53
	v_exp_f32_e32 v54, v54
	v_exp_f32_e32 v55, v55
	v_exp_f32_e32 v56, v56
	v_exp_f32_e32 v57, v57
	v_cvt_pk_bf16_f32 v118, v50, v51
	v_cvt_pk_bf16_f32 v119, v52, v53
	v_cvt_pk_bf16_f32 v120, v54, v55
	v_cvt_pk_bf16_f32 v121, v56, v57
	v_pk_add_f32 v[50:51], v[50:51], v[52:53]
	v_pk_add_f32 v[54:55], v[54:55], v[56:57]
	v_pk_add_f32 v[50:51], v[50:51], v[54:55]
	v_pk_add_f32 v[116:117], v[116:117], v[50:51]
	v_mfma_f32_32x32x16_bf16 v[18:33], v[140:143], v[118:121], v[18:33]
	v_mfma_f32_32x32x16_bf16 v[2:17], v[144:147], v[118:121], v[2:17]
	v_pk_add_f32 v[58:59], v[58:59], v[0:1] op_sel_hi:[1,0] neg_lo:[0,1] neg_hi:[0,1]
	v_pk_add_f32 v[60:61], v[60:61], v[0:1] op_sel_hi:[1,0] neg_lo:[0,1] neg_hi:[0,1]
	v_pk_add_f32 v[62:63], v[62:63], v[0:1] op_sel_hi:[1,0] neg_lo:[0,1] neg_hi:[0,1]
	v_pk_add_f32 v[64:65], v[64:65], v[0:1] op_sel_hi:[1,0] neg_lo:[0,1] neg_hi:[0,1]
	v_exp_f32_e32 v58, v58
	v_exp_f32_e32 v59, v59
	v_exp_f32_e32 v60, v60
	v_exp_f32_e32 v61, v61
	v_exp_f32_e32 v62, v62
	v_exp_f32_e32 v63, v63
	v_exp_f32_e32 v64, v64
	v_exp_f32_e32 v65, v65
	v_cvt_pk_bf16_f32 v118, v58, v59
	v_cvt_pk_bf16_f32 v119, v60, v61
	v_cvt_pk_bf16_f32 v120, v62, v63
	v_cvt_pk_bf16_f32 v121, v64, v65
	v_pk_add_f32 v[58:59], v[58:59], v[60:61]
	v_pk_add_f32 v[62:63], v[62:63], v[64:65]
	v_pk_add_f32 v[58:59], v[58:59], v[62:63]
	v_pk_add_f32 v[116:117], v[116:117], v[58:59]
	v_mfma_f32_32x32x16_bf16 v[18:33], v[148:151], v[118:121], v[18:33]
	v_mfma_f32_32x32x16_bf16 v[2:17], v[152:155], v[118:121], v[2:17]
	v_add_f32_e32 v116, v116, v117
	v_add_f32_e32 v109, v109, v116
	v_mov_b32_e32 v114, v0

; #define LAS __attribute__((address_space(3)))
; __device__ __forceinline__ int fresh_tid() { int t = threadIdx.x; asm volatile("" : "+v"(t)); return t; }
; __device__ __forceinline__ void attn_load(const AttnJob& J, int t, u32x4& kreg, u32x4& vreg) {
;     const int tid = fresh_tid(), key = tid >> 3, ch = tid & 7, kidx = 64 * t + key;
;     if (J.mode == 0) { const bf16_t* p = J.Kb + (size_t)kidx * 2048 + ch * 8; kreg = *(const u32x4*)p; vreg = *(const u32x4*)(p + 512); }
;     else if (kidx < PAST) { const float* pk = J.cK + (size_t)kidx * 512 + ch * 8; const float* pv = J.cV + (size_t)kidx * 512 + ch * 8;
;         const f32x4 a = *(const f32x4*)pk, b = *(const f32x4*)(pk + 4), c = *(const f32x4*)pv, d = *(const f32x4*)(pv + 4);
;         kreg = (u32x4){pk_bf16(a.x, a.y), pk_bf16(a.z, a.w), pk_bf16(b.x, b.y), pk_bf16(b.z, b.w)};
;         vreg = (u32x4){pk_bf16(c.x, c.y), pk_bf16(c.z, c.w), pk_bf16(d.x, d.y), pk_bf16(d.z, d.w)}; }
;     else if (kidx < PAST + TS) { const bf16_t* p = J.Kb + (size_t)(kidx - PAST) * 2048 + ch * 8; kreg = *(const u32x4*)p; vreg = *(const u32x4*)(p + 512); }
;     else { kreg = (u32x4){0u, 0u, 0u, 0u}; vreg = kreg; }
; }
; __device__ __forceinline__ void attn_stage(LAS unsigned char* lds, int buf, const u32x4& kreg, const u32x4& vreg) {
;     const int tid = fresh_tid(), key = tid >> 3, ch = tid & 7;
;     *(LAS u32x4*)(lds + AT_K + buf * AT_KB + key * 144 + ch * 16) = kreg;
;     LAS bf16_t* vt = (LAS bf16_t*)(lds + AT_VT + buf * AT_VB) + (ch * 8) * 68 + key;
;     vt[0 * 68] = (bf16_t)(vreg.x & 0xffffu); vt[1 * 68] = (bf16_t)(vreg.x >> 16);
;     vt[2 * 68] = (bf16_t)(vreg.y & 0xffffu); vt[3 * 68] = (bf16_t)(vreg.y >> 16);
;     vt[4 * 68] = (bf16_t)(vreg.z & 0xffffu); vt[5 * 68] = (bf16_t)(vreg.z >> 16);
;     vt[6 * 68] = (bf16_t)(vreg.w & 0xffffu); vt[7 * 68] = (bf16_t)(vreg.w >> 16);
; }
; __device__ __forceinline__ void attn_unit(const AttnJob& J, LAS unsigned char* lds) {
;     ...
;     for (int t = 0; t < J.NT; t += 2) {
;         attn_stage(lds, 0, kA, vA);
;         __syncthreads();
;         if (t + 2 < J.NT) attn_load(J, t + 2, kA, vA);
;         if (active && 64 * t <= qlo + 31) attn_tile(t, 0, lds, qr, cq2, qlo, qpos, q32, hi, mrun, lrun, o0, o1);
;         if (t + 1 < J.NT) {
;             attn_stage(lds, 1, kB, vB);
;             __syncthreads();
;             if (t + 3 < J.NT) attn_load(J, t + 3, kB, vB);
.LBB0_645:
	s_add_i32 s26, s22, -1
	s_cmp_ge_u32 s26, s20
	s_waitcnt vmcnt(1)
	ds_write_b128 v156, v[82:85] offset:8448
	s_waitcnt vmcnt(0)
	ds_write_b16 v157, v86 offset:26880
	ds_write_b16_d16_hi v157, v86 offset:27016
	ds_write_b16 v157, v87 offset:27152
	ds_write_b16_d16_hi v157, v87 offset:27288
	ds_write_b16 v157, v88 offset:27424
	ds_write_b16_d16_hi v157, v88 offset:27560
	ds_write_b16 v157, v89 offset:27696
	ds_write_b16_d16_hi v157, v89 offset:27832
	s_waitcnt lgkmcnt(0)
	s_barrier
	s_cbranch_scc1 .LBB0_647
	s_lshl_b64 s[98:99], s[14:15], 12
	s_add_u32 s98, s98, s8
	s_addc_u32 s99, s99, s9
	s_add_u32 s98, s98, 0xfffc0000
	s_addc_u32 s99, s99, -1
	v_lshl_add_u64 v[34:35], s[98:99], 0, v[158:159]
	global_load_dwordx4 v[82:85], v[34:35], off offset:1024
	global_load_dwordx4 v[86:89], v[34:35], off offset:2048

; __device__ __forceinline__ float fexp2(float x) { return __builtin_amdgcn_exp2f(x); }
; __device__ __forceinline__ void attn_tile(int t, int buf, LAS unsigned char* lds, const bf16x8 (&qr)[4], float cq2, int qlo, int qpos, int q32, int hi,
;                                           float& mrun, float& lrun, f32x16& o0, f32x16& o1) {
;     ...
;     float mx = fmaxf(s0[0], s1[0]);
; #pragma unroll
;     for (int r = 1; r < 16; ++r) mx = fmaxf(mx, fmaxf(s0[r], s1[r]));
;     mx = fmaxf(mx, __shfl_xor(mx, 32));
;     const float mnew = fmaxf(mrun, mx);
;     if (__any(mnew > mrun)) {
;         const float alpha = fexp2(mrun - mnew); lrun *= alpha;
; #pragma unroll
;         for (int r = 0; r < 16; ++r) { o0[r] *= alpha; o1[r] *= alpha; }
;     }
;     mrun = mnew;
.LBB0_651:
	s_nop 10
	v_max3_f32 v0, v34, v50, v35
	v_max3_f32 v115, v51, v36, v52
	v_max3_f32 v0, v0, v37, v53
	v_max3_f32 v115, v115, v38, v54
	v_max3_f32 v0, v0, v39, v55
	v_max3_f32 v115, v115, v40, v56
	v_max3_f32 v0, v0, v41, v57
	v_max3_f32 v115, v115, v42, v58
	v_max3_f32 v0, v0, v43, v59
	v_max3_f32 v115, v115, v44, v60
	v_max3_f32 v0, v0, v45, v61
	v_max3_f32 v115, v115, v46, v62
	v_max3_f32 v0, v0, v47, v63
	v_max3_f32 v115, v115, v48, v64
	v_max3_f32 v0, v0, v49, v65
	v_max_f32_e32 v0, v0, v115
	ds_bpermute_b32 v115, v107, v0
	s_waitcnt lgkmcnt(0)
	v_max3_f32 v0, v114, v0, v115
	v_add_f32_e32 v115, 0x41c00000, v114
	v_cmp_gt_f32_e32 vcc, v0, v115
	s_cbranch_vccnz .Lresc_a
	v_mov_b32_e32 v0, v114
	s_branch .LBB0_653
.Lresc_a:
	v_sub_f32_e32 v114, v114, v0
	v_exp_f32_e32 v114, v114
	s_nop 0
	v_mul_f32_e32 v109, v109, v114
	v_pk_mul_f32 v[32:33], v[32:33], v[114:115] op_sel_hi:[1,0]
	v_pk_mul_f32 v[30:31], v[30:31], v[114:115] op_sel_hi:[1,0]
	v_pk_mul_f32 v[28:29], v[28:29], v[114:115] op_sel_hi:[1,0]
	v_pk_mul_f32 v[26:27], v[26:27], v[114:115] op_sel_hi:[1,0]
	v_pk_mul_f32 v[24:25], v[24:25], v[114:115] op_sel_hi:[1,0]
	v_pk_mul_f32 v[22:23], v[22:23], v[114:115] op_sel_hi:[1,0]
	v_pk_mul_f32 v[20:21], v[20:21], v[114:115] op_sel_hi:[1,0]
	v_pk_mul_f32 v[18:19], v[18:19], v[114:115] op_sel_hi:[1,0]
	v_pk_mul_f32 v[16:17], v[16:17], v[114:115] op_sel_hi:[1,0]
	v_pk_mul_f32 v[14:15], v[14:15], v[114:115] op_sel_hi:[1,0]
	v_pk_mul_f32 v[12:13], v[12:13], v[114:115] op_sel_hi:[1,0]
	v_pk_mul_f32 v[10:11], v[10:11], v[114:115] op_sel_hi:[1,0]
	v_pk_mul_f32 v[8:9], v[8:9], v[114:115] op_sel_hi:[1,0]
	v_pk_mul_f32 v[6:7], v[6:7], v[114:115] op_sel_hi:[1,0]
	v_pk_mul_f32 v[4:5], v[4:5], v[114:115] op_sel_hi:[1,0]
	v_pk_mul_f32 v[2:3], v[2:3], v[114:115] op_sel_hi:[1,0]
; #define LAS __attribute__((address_space(3)))
; __device__ __forceinline__ float fexp2(float x) { return __builtin_amdgcn_exp2f(x); }
; __device__ __forceinline__ void attn_tile(int t, int buf, LAS unsigned char* lds, const bf16x8 (&qr)[4], float cq2, int qlo, int qpos, int q32, int hi,
;                                           float& mrun, float& lrun, f32x16& o0, f32x16& o1) {
;     ...
;     f32x2 ls2 = (f32x2){0.f, 0.f};
; #pragma unroll
;     for (int r = 0; r < 16; r += 2) {
;         const f32x2 d0 = (f32x2){s0[r], s0[r + 1]} - mnew, d1 = (f32x2){s1[r], s1[r + 1]} - mnew;
;         f32x2 e0, e1; e0.x = fexp2(d0.x); e0.y = fexp2(d0.y); e1.x = fexp2(d1.x); e1.y = fexp2(d1.y);
;         s0[r] = e0.x; s0[r + 1] = e0.y; s1[r] = e1.x; s1[r + 1] = e1.y;
;         ls2 += e0 + e1;
;     }
;     lrun += ls2.x + ls2.y;
; #pragma unroll
;     for (int p = 0; p < 2; ++p)
; #pragma unroll
;         for (int sx = 0; sx < 2; ++sx) {
;             u32x4 pw;
;             if (p == 0) pw = (u32x4){pk_bf16(s0[8 * sx + 0], s0[8 * sx + 1]), pk_bf16(s0[8 * sx + 2], s0[8 * sx + 3]), pk_bf16(s0[8 * sx + 4], s0[8 * sx + 5]), pk_bf16(s0[8 * sx + 6], s0[8 * sx + 7])};
;             else        pw = (u32x4){pk_bf16(s1[8 * sx + 0], s1[8 * sx + 1]), pk_bf16(s1[8 * sx + 2], s1[8 * sx + 3]), pk_bf16(s1[8 * sx + 4], s1[8 * sx + 5]), pk_bf16(s1[8 * sx + 6], s1[8 * sx + 7])};
;             const bf16x8 pf = __builtin_bit_cast(bf16x8, pw);
;             const int ko = (32 * p + 16 * sx + 4 * hi) * 2;
;             const u32x2 a0 = *(const LAS u32x2*)(Vt + q32 * 136 + ko), a1 = *(const LAS u32x2*)(Vt + q32 * 136 + ko + 16);
;             const u32x2 b0 = *(const LAS u32x2*)(Vt + (32 + q32) * 136 + ko), b1 = *(const LAS u32x2*)(Vt + (32 + q32) * 136 + ko + 16);
;             const bf16x8 vf0 = __builtin_bit_cast(bf16x8, (u32x4){a0.x, a0.y, a1.x, a1.y});
;             const bf16x8 vf1 = __builtin_bit_cast(bf16x8, (u32x4){b0.x, b0.y, b1.x, b1.y});
;             o0 = __builtin_amdgcn_mfma_f32_32x32x16_bf16(vf0, pf, o0, 0, 0, 0);
;             o1 = __builtin_amdgcn_mfma_f32_32x32x16_bf16(vf1, pf, o1, 0, 0, 0);
;         }
; __device__ __forceinline__ void attn_unit(const AttnJob& J, LAS unsigned char* lds) {
;     ...
;         if (t + 1 < J.NT) {
;             attn_stage(lds, 1, kB, vB);
;             __syncthreads();
;             if (t + 3 < J.NT) attn_load(J, t + 3, kB, vB);
.LBB0_653:
	v_add_u32_e32 v122, 0x6800, v113
	v_add_u32_e32 v123, 0x7800, v113
	ds_read2_b64 v[124:127], v122 offset0:32 offset1:34
	ds_read2_b64 v[128:131], v123 offset0:64 offset1:66
	ds_read2_b64 v[132:135], v122 offset0:36 offset1:38
	ds_read2_b64 v[136:139], v123 offset0:68 offset1:70
	ds_read2_b64 v[140:143], v122 offset0:40 offset1:42
	ds_read2_b64 v[144:147], v123 offset0:72 offset1:74
	ds_read2_b64 v[148:151], v122 offset0:44 offset1:46
	ds_read2_b64 v[152:155], v123 offset0:76 offset1:78
	v_pk_add_f32 v[34:35], v[34:35], v[0:1] op_sel_hi:[1,0] neg_lo:[0,1] neg_hi:[0,1]
	v_pk_add_f32 v[36:37], v[36:37], v[0:1] op_sel_hi:[1,0] neg_lo:[0,1] neg_hi:[0,1]
	v_pk_add_f32 v[38:39], v[38:39], v[0:1] op_sel_hi:[1,0] neg_lo:[0,1] neg_hi:[0,1]
	v_pk_add_f32 v[40:41], v[40:41], v[0:1] op_sel_hi:[1,0] neg_lo:[0,1] neg_hi:[0,1]
	v_exp_f32_e32 v34, v34
	v_exp_f32_e32 v35, v35
	v_exp_f32_e32 v36, v36
	v_exp_f32_e32 v37, v37
	v_exp_f32_e32 v38, v38
	v_exp_f32_e32 v39, v39
	v_exp_f32_e32 v40, v40
	v_exp_f32_e32 v41, v41
	v_cvt_pk_bf16_f32 v118, v34, v35
	v_cvt_pk_bf16_f32 v119, v36, v37
	v_cvt_pk_bf16_f32 v120, v38, v39
	v_cvt_pk_bf16_f32 v121, v40, v41
	v_pk_add_f32 v[116:117], v[34:35], v[36:37]
	v_pk_add_f32 v[38:39], v[38:39], v[40:41]
	v_pk_add_f32 v[116:117], v[116:117], v[38:39]
	s_waitcnt lgkmcnt(0)
	v_mfma_f32_32x32x16_bf16 v[18:33], v[124:127], v[118:121], v[18:33]
	v_mfma_f32_32x32x16_bf16 v[2:17], v[128:131], v[118:121], v[2:17]
	v_pk_add_f32 v[42:43], v[42:43], v[0:1] op_sel_hi:[1,0] neg_lo:[0,1] neg_hi:[0,1]
	v_pk_add_f32 v[44:45], v[44:45], v[0:1] op_sel_hi:[1,0] neg_lo:[0,1] neg_hi:[0,1]
	v_pk_add_f32 v[46:47], v[46:47], v[0:1] op_sel_hi:[1,0] neg_lo:[0,1] neg_hi:[0,1]
	v_pk_add_f32 v[48:49], v[48:49], v[0:1] op_sel_hi:[1,0] neg_lo:[0,1] neg_hi:[0,1]
	v_exp_f32_e32 v42, v42
	v_exp_f32_e32 v43, v43
	v_exp_f32_e32 v44, v44
	v_exp_f32_e32 v45, v45
	v_exp_f32_e32 v46, v46
	v_exp_f32_e32 v47, v47
	v_exp_f32_e32 v48, v48
	v_exp_f32_e32 v49, v49
	v_cvt_pk_bf16_f32 v118, v42, v43
	v_cvt_pk_bf16_f32 v119, v44, v45
	v_cvt_pk_bf16_f32 v120, v46, v47
	v_cvt_pk_bf16_f32 v121, v48, v49
	v_pk_add_f32 v[42:43], v[42:43], v[44:45]
	v_pk_add_f32 v[46:47], v[46:47], v[48:49]
	v_pk_add_f32 v[42:43], v[42:43], v[46:47]
	v_pk_add_f32 v[116:117], v[116:117], v[42:43]
	v_mfma_f32_32x32x16_bf16 v[18:33], v[132:135], v[118:121], v[18:33]
	v_mfma_f32_32x32x16_bf16 v[2:17], v[136:139], v[118:121], v[2:17]
	v_pk_add_f32 v[50:51], v[50:51], v[0:1] op_sel_hi:[1,0] neg_lo:[0,1] neg_hi:[0,1]
	v_pk_add_f32 v[52:53], v[52:53], v[0:1] op_sel_hi:[1,0] neg_lo:[0,1] neg_hi:[0,1]
	v_pk_add_f32 v[54:55], v[54:55], v[0:1] op_sel_hi:[1,0] neg_lo:[0,1] neg_hi:[0,1]
	v_pk_add_f32 v[56:57], v[56:57], v[0:1] op_sel_hi:[1,0] neg_lo:[0,1] neg_hi:[0,1]
	v_exp_f32_e32 v50, v50
	v_exp_f32_e32 v51, v51
	v_exp_f32_e32 v52, v52
	v_exp_f32_e32 v53, v53
	v_exp_f32_e32 v54, v54
	v_exp_f32_e32 v55, v55
	v_exp_f32_e32 v56, v56
	v_exp_f32_e32 v57, v57
	v_cvt_pk_bf16_f32 v118, v50, v51
	v_cvt_pk_bf16_f32 v119, v52, v53
	v_cvt_pk_bf16_f32 v120, v54, v55
	v_cvt_pk_bf16_f32 v121, v56, v57
	v_pk_add_f32 v[50:51], v[50:51], v[52:53]
	v_pk_add_f32 v[54:55], v[54:55], v[56:57]
	v_pk_add_f32 v[50:51], v[50:51], v[54:55]
	v_pk_add_f32 v[116:117], v[116:117], v[50:51]
	v_mfma_f32_32x32x16_bf16 v[18:33], v[140:143], v[118:121], v[18:33]
	v_mfma_f32_32x32x16_bf16 v[2:17], v[144:147], v[118:121], v[2:17]
	v_pk_add_f32 v[58:59], v[58:59], v[0:1] op_sel_hi:[1,0] neg_lo:[0,1] neg_hi:[0,1]
	v_pk_add_f32 v[60:61], v[60:61], v[0:1] op_sel_hi:[1,0] neg_lo:[0,1] neg_hi:[0,1]
	v_pk_add_f32 v[62:63], v[62:63], v[0:1] op_sel_hi:[1,0] neg_lo:[0,1] neg_hi:[0,1]
	v_pk_add_f32 v[64:65], v[64:65], v[0:1] op_sel_hi:[1,0] neg_lo:[0,1] neg_hi:[0,1]
	v_exp_f32_e32 v58, v58
	v_exp_f32_e32 v59, v59
	v_exp_f32_e32 v60, v60
	v_exp_f32_e32 v61, v61
	v_exp_f32_e32 v62, v62
	v_exp_f32_e32 v63, v63
	v_exp_f32_e32 v64, v64
	v_exp_f32_e32 v65, v65
	v_cvt_pk_bf16_f32 v118, v58, v59
	v_cvt_pk_bf16_f32 v119, v60, v61
	v_cvt_pk_bf16_f32 v120, v62, v63
	v_cvt_pk_bf16_f32 v121, v64, v65
	v_pk_add_f32 v[58:59], v[58:59], v[60:61]
	v_pk_add_f32 v[62:63], v[62:63], v[64:65]
	v_pk_add_f32 v[58:59], v[58:59], v[62:63]
	v_pk_add_f32 v[116:117], v[116:117], v[58:59]
	v_mfma_f32_32x32x16_bf16 v[18:33], v[148:151], v[118:121], v[18:33]
	v_mfma_f32_32x32x16_bf16 v[2:17], v[152:155], v[118:121], v[2:17]
	v_add_f32_e32 v116, v116, v117
	v_add_f32_e32 v109, v109, v116
	v_mov_b32_e32 v114, v0
.LBB0_654:
	s_add_i32 s27, s22, -2
	s_cmp_ge_u32 s27, s20
	s_cbranch_scc1 .LBB0_644
	s_cmp_ge_u32 s22, s20
	s_waitcnt vmcnt(1)
	ds_write_b128 v156, v[90:93] offset:17664
	s_waitcnt vmcnt(0)
	ds_write_b16 v157, v94 offset:35584
	ds_write_b16_d16_hi v157, v94 offset:35720
	ds_write_b16 v157, v95 offset:35856
	ds_write_b16_d16_hi v157, v95 offset:35992
	ds_write_b16 v157, v96 offset:36128
	ds_write_b16_d16_hi v157, v96 offset:36264
	ds_write_b16 v157, v97 offset:36400
	ds_write_b16_d16_hi v157, v97 offset:36536
	s_waitcnt lgkmcnt(0)
	s_barrier
	s_cbranch_scc1 .LBB0_657
	s_lshl_b64 s[98:99], s[14:15], 12
	s_add_u32 s98, s98, s8
	s_addc_u32 s99, s99, s9
	v_lshl_add_u64 v[34:35], s[98:99], 0, v[158:159]
	global_load_dwordx4 v[90:93], v[34:35], off offset:1024
	global_load_dwordx4 v[94:97], v[34:35], off offset:2048

; __device__ __forceinline__ float fexp2(float x) { return __builtin_amdgcn_exp2f(x); }
; __device__ __forceinline__ void attn_tile(int t, int buf, LAS unsigned char* lds, const bf16x8 (&qr)[4], float cq2, int qlo, int qpos, int q32, int hi,
;                                           float& mrun, float& lrun, f32x16& o0, f32x16& o1) {
;     ...
;     if (__any(mnew > mrun)) {
;         const float alpha = fexp2(mrun - mnew); lrun *= alpha;
; #pragma unroll
;         for (int r = 0; r < 16; ++r) { o0[r] *= alpha; o1[r] *= alpha; }
;     }
.Lresc_b:
	v_sub_f32_e32 v114, v114, v0
	v_exp_f32_e32 v114, v114
	s_nop 0
	v_mul_f32_e32 v109, v109, v114
	v_pk_mul_f32 v[32:33], v[32:33], v[114:115] op_sel_hi:[1,0]
	v_pk_mul_f32 v[30:31], v[30:31], v[114:115] op_sel_hi:[1,0]
	v_pk_mul_f32 v[28:29], v[28:29], v[114:115] op_sel_hi:[1,0]
	v_pk_mul_f32 v[26:27], v[26:27], v[114:115] op_sel_hi:[1,0]
	v_pk_mul_f32 v[24:25], v[24:25], v[114:115] op_sel_hi:[1,0]
	v_pk_mul_f32 v[22:23], v[22:23], v[114:115] op_sel_hi:[1,0]
	v_pk_mul_f32 v[20:21], v[20:21], v[114:115] op_sel_hi:[1,0]
	v_pk_mul_f32 v[18:19], v[18:19], v[114:115] op_sel_hi:[1,0]
	v_pk_mul_f32 v[16:17], v[16:17], v[114:115] op_sel_hi:[1,0]
	v_pk_mul_f32 v[14:15], v[14:15], v[114:115] op_sel_hi:[1,0]
	v_pk_mul_f32 v[12:13], v[12:13], v[114:115] op_sel_hi:[1,0]
	v_pk_mul_f32 v[10:11], v[10:11], v[114:115] op_sel_hi:[1,0]
	v_pk_mul_f32 v[8:9], v[8:9], v[114:115] op_sel_hi:[1,0]
	v_pk_mul_f32 v[6:7], v[6:7], v[114:115] op_sel_hi:[1,0]
	v_pk_mul_f32 v[4:5], v[4:5], v[114:115] op_sel_hi:[1,0]
	v_pk_mul_f32 v[2:3], v[2:3], v[114:115] op_sel_hi:[1,0]
	s_branch .LBB0_643

; __device__ __forceinline__ int fresh_tid() { int t = threadIdx.x; asm volatile("" : "+v"(t)); return t; }
; __global__ void __launch_bounds__(512) fwd_megakernel(Args a) {
;     ...
;                 for (int bh = bx; bh < 256; bh += G) {
;                     const int b = bh >> 3, h = bh & 7;
;                     { const float* lf = out + OFF_FP + (size_t)b * SEQ * 8 + h; const int t = 4 * fresh_tid();
;                       scan2048(lf[(size_t)(t + 0) * 8], lf[(size_t)(t + 1) * 8], lf[(size_t)(t + 2) * 8], lf[(size_t)(t + 3) * 8], lds); }
;     ...
;                         AttnJob J; J.Qrow0 = R1 + (size_t)(b * SEQ + qb * 256) * 2048 + h * 64; J.Orow0 = MIX + (size_t)(b * SEQ + qb * 256) * DM + h * 64;
;                         J.nqw = 8; J.qpos0 = qb * 256; J.NT = 4 * (qb + 1); J.mode = 0; J.Kb = R1 + (size_t)(b * SEQ) * 2048 + 512 + h * 64; J.cK = nullptr; J.cV = nullptr;
;                         attn_unit(J, lds);
;                     }
;                 }
;                 for (int bh = bx; bh < 256; bh += G) {
;                     const int b = bh >> 3, h = bh & 7;
;                     { const float* cf = a.in[4] + (size_t)b * PAST * 8 + h; const float* nf = out + OFF_FS + (size_t)b * TS * 8 + h; float v[4]; const int tid = fresh_tid();
; #pragma unroll
;                       for (int e = 0; e < 4; ++e) { const int t = 4 * tid + e; v[e] = t < PAST ? cf[(size_t)t * 8] : (t < PAST + TS ? nf[(size_t)(t - PAST) * 8] : 0.f); }
;                       scan2048(v[0], v[1], v[2], v[3], lds); }
;                     AttnJob J; J.Qrow0 = R1 + (size_t)(MP + b * TS) * 2048 + h * 64; J.Orow0 = MIX + (size_t)(MP + b * TS) * DM + h * 64;
;                     J.nqw = 1; J.qpos0 = PAST; J.NT = 17; J.mode = 1; J.Kb = R1 + (size_t)(MP + b * TS) * 2048 + 512 + h * 64;
;                     J.cK = a.in[2] + (size_t)b * PAST * 512 + h * 64; J.cV = a.in[3] + (size_t)b * PAST * 512 + h * 64;
;                     attn_unit(J, lds);
;                 }
.LBB0_673:
	v_lshrrev_b32_e32 v0, 6, v198
	v_mul_u32_u24_e32 v0, 0x300, v0
	v_and_or_b32 v0, v198, 63, v0
	v_lshlrev_b32_e32 v0, 4, v0
	ds_read_b128 v[124:127], v0 offset:45056
	ds_read_b128 v[128:131], v0 offset:46080
	ds_read_b128 v[132:135], v0 offset:47104
	ds_read_b128 v[136:139], v0 offset:48128
	ds_read_b128 v[140:143], v0 offset:49152
	ds_read_b128 v[144:147], v0 offset:50176
	ds_read_b128 v[148:151], v0 offset:51200
	ds_read_b128 v[152:155], v0 offset:52224
	ds_read_b128 v[156:159], v0 offset:53248
	s_waitcnt lgkmcnt(0)
	s_mov_b32 s70, s2
	s_branch .LBB0_676
